# gMLP staging: 16-lane row sums by DPP (quad_perm, row_half_mirror, row_mirror) instead of four serialized ds_bpermute round trips
# speedup vs baseline: 1.0081x; 1.0081x over previous
; #define LAS __attribute__((address_space(3)))
; __device__ __forceinline__ unsigned cvt_pk_bf16(float lo, float hi) { unsigned r; asm volatile("v_cvt_pk_bf16_f32 %0, %1, %2" : "=v"(r) : "v"(lo), "v"(hi)); return r; }
; __device__ __forceinline__ float bflo(unsigned w) { return __uint_as_float(w << 16); }
; __device__ __forceinline__ float bfhi(unsigned w) { return __uint_as_float(w & 0xffff0000u); }
; __device__ __forceinline__ void sgu_run(LAS unsigned char* lds, bf16_t* P, const bf16_t* wsb, const float* bs, const float* sg, const float* ssv, int ch0, int cstep, int h, int tid, int lane, int wid, bool dry) {
;     ...
;         for (int i = 0; i < 4; ++i) {
;             const int idx = tid + 512 * i, r = idx >> 4, c16 = idx & 15;
;             float pt = part[i];
;             pt += __shfl_xor(pt, 1); pt += __shfl_xor(pt, 2); pt += __shfl_xor(pt, 4); pt += __shfl_xor(pt, 8);
;             const float rv = __builtin_amdgcn_rsqf(pt * (1.0f / 1024.0f) + EPS);
;             const f32x4 g0 = sg0 * rv, g1 = sg1 * rv;
;             u32x4 gn;
;             gn.x = cvt_pk_bf16(bflo(gv[i].x) * g0[0], bfhi(gv[i].x) * g0[1]); gn.y = cvt_pk_bf16(bflo(gv[i].y) * g0[2], bfhi(gv[i].y) * g0[3]);
;             gn.z = cvt_pk_bf16(bflo(gv[i].z) * g1[0], bfhi(gv[i].z) * g1[1]); gn.w = cvt_pk_bf16(bflo(gv[i].w) * g1[2], bfhi(gv[i].w) * g1[3]);
;             *(LAS u32x4*)(GV + r * 288 + c16 * 16) = gn;
;             *(LAS u32x4*)(GU + r * 272 + c16 * 16) = gu[i];
;             *(LAS u32x4*)(SZ + r * 272 + c16 * 16) = sz[i];
;             if (first) *(LAS u32x4*)(WT + r * 272 + c16 * 16) = *(const u32x4*)(wsb + ((size_t)(h * 128 + r) * 128 + c16 * 8));
.LBB0_49:
	s_waitcnt vmcnt(14)
	v_add_u32_e32 v154, v129, v134
	s_andn2_b64 vcc, exec, s[82:83]
	s_waitcnt lgkmcnt(0)
	s_nop 1
	v_add_f32_dpp v56, v120, v120 quad_perm:[1,0,3,2] row_mask:0xf bank_mask:0xf
	s_waitcnt lgkmcnt(0)
	s_nop 1
	v_add_f32_dpp v57, v56, v56 quad_perm:[2,3,0,1] row_mask:0xf bank_mask:0xf
	v_mov_b32_e32 v56, v57
	s_waitcnt lgkmcnt(0)
	s_nop 1
	v_add_f32_dpp v57, v56, v56 row_half_mirror row_mask:0xf bank_mask:0xf
	v_mov_b32_e32 v56, v57
	s_waitcnt lgkmcnt(0)
	s_nop 1
	v_add_f32_dpp v57, v56, v56 row_mirror row_mask:0xf bank_mask:0xf
	v_mov_b32_e32 v56, v57
	v_fmamk_f32 v56, v56, 0x3a800000, v217
	v_rsq_f32_e32 v56, v56
	s_waitcnt vmcnt(0)
	v_pk_mul_f32 v[58:59], v[54:55], v[56:57] op_sel_hi:[1,0]
	v_pk_mul_f32 v[60:61], v[52:53], v[56:57] op_sel_hi:[1,0]
	v_pk_mul_f32 v[62:63], v[50:51], v[56:57] op_sel_hi:[1,0]
	v_pk_mul_f32 v[64:65], v[48:49], v[56:57] op_sel_hi:[1,0]
	v_lshlrev_b32_e32 v56, 16, v0
	v_and_b32_e32 v57, 0xffff0000, v0
	v_mul_f32_e32 v56, v60, v56
	v_mul_f32_e32 v57, v61, v57
	v_cvt_pk_bf16_f32 v56, v56, v57
	v_lshlrev_b32_e32 v57, 16, v1
	v_mul_f32_e32 v57, v58, v57
	v_and_b32_e32 v58, 0xffff0000, v1
	v_mul_f32_e32 v58, v59, v58
	v_cvt_pk_bf16_f32 v57, v57, v58
	v_lshlrev_b32_e32 v58, 16, v2
	v_and_b32_e32 v59, 0xffff0000, v2
	v_mul_f32_e32 v58, v64, v58
	v_mul_f32_e32 v59, v65, v59
	v_cvt_pk_bf16_f32 v58, v58, v59
	v_lshlrev_b32_e32 v59, 16, v3
	v_mul_f32_e32 v59, v62, v59
	v_and_b32_e32 v60, 0xffff0000, v3
	v_mul_f32_e32 v60, v63, v60
	v_cvt_pk_bf16_f32 v59, v59, v60
	ds_write_b128 v149, v[56:59]
	v_add_u32_e32 v56, v130, v134
	ds_write_b128 v56, v[8:11]
	v_cndmask_b32_e64 v56, 0, 1, s[82:83]
	v_cmp_ne_u32_e64 s[38:39], 1, v56
	ds_write_b128 v154, v[4:7]
	s_cbranch_vccnz .LBB0_51
	global_load_dwordx4 v[56:59], v[100:101], off
	v_add_u32_e32 v60, v128, v134
	s_waitcnt vmcnt(0)
	ds_write_b128 v60, v[56:59] offset:36864
.LBB0_51:
	v_add_u32_e32 v155, v129, v135
	s_and_b64 vcc, exec, s[38:39]
	s_waitcnt lgkmcnt(0)
	s_nop 1
	v_add_f32_dpp v56, v121, v121 quad_perm:[1,0,3,2] row_mask:0xf bank_mask:0xf
	s_waitcnt lgkmcnt(0)
	s_nop 1
	v_add_f32_dpp v57, v56, v56 quad_perm:[2,3,0,1] row_mask:0xf bank_mask:0xf
	v_mov_b32_e32 v56, v57
	s_waitcnt lgkmcnt(0)
	s_nop 1
	v_add_f32_dpp v57, v56, v56 row_half_mirror row_mask:0xf bank_mask:0xf
	v_mov_b32_e32 v56, v57
	s_waitcnt lgkmcnt(0)
	s_nop 1
	v_add_f32_dpp v57, v56, v56 row_mirror row_mask:0xf bank_mask:0xf
	v_mov_b32_e32 v56, v57
	v_fmamk_f32 v56, v56, 0x3a800000, v217
	v_rsq_f32_e32 v56, v56
	s_nop 0
	v_pk_mul_f32 v[58:59], v[54:55], v[56:57] op_sel_hi:[1,0]
	v_pk_mul_f32 v[60:61], v[52:53], v[56:57] op_sel_hi:[1,0]
	v_pk_mul_f32 v[62:63], v[50:51], v[56:57] op_sel_hi:[1,0]
	v_pk_mul_f32 v[64:65], v[48:49], v[56:57] op_sel_hi:[1,0]
	v_lshlrev_b32_e32 v56, 16, v16
	v_and_b32_e32 v57, 0xffff0000, v16
	v_mul_f32_e32 v56, v60, v56
	v_mul_f32_e32 v57, v61, v57
	v_cvt_pk_bf16_f32 v56, v56, v57
	v_lshlrev_b32_e32 v57, 16, v17
	v_mul_f32_e32 v57, v58, v57
	v_and_b32_e32 v58, 0xffff0000, v17
	v_mul_f32_e32 v58, v59, v58
	v_cvt_pk_bf16_f32 v57, v57, v58
	v_lshlrev_b32_e32 v58, 16, v18
	v_and_b32_e32 v59, 0xffff0000, v18
	v_mul_f32_e32 v58, v64, v58
	v_mul_f32_e32 v59, v65, v59
	v_cvt_pk_bf16_f32 v58, v58, v59
	v_lshlrev_b32_e32 v59, 16, v19
	v_mul_f32_e32 v59, v62, v59
	v_and_b32_e32 v60, 0xffff0000, v19
	v_mul_f32_e32 v60, v63, v60
	v_cvt_pk_bf16_f32 v59, v59, v60
	ds_write_b128 v150, v[56:59]
	v_add_u32_e32 v56, v130, v135
	ds_write_b128 v155, v[12:15]
	ds_write_b128 v56, v[20:23]
	s_cbranch_vccnz .LBB0_53
	global_load_dwordx4 v[56:59], v[102:103], off
	v_add_u32_e32 v60, v128, v135
	s_waitcnt vmcnt(0)
	ds_write_b128 v60, v[56:59] offset:36864
; #define LAS __attribute__((address_space(3)))
; __device__ __forceinline__ unsigned cvt_pk_bf16(float lo, float hi) { unsigned r; asm volatile("v_cvt_pk_bf16_f32 %0, %1, %2" : "=v"(r) : "v"(lo), "v"(hi)); return r; }
; __device__ __forceinline__ float bflo(unsigned w) { return __uint_as_float(w << 16); }
; __device__ __forceinline__ float bfhi(unsigned w) { return __uint_as_float(w & 0xffff0000u); }
; __device__ __forceinline__ void sgu_run(LAS unsigned char* lds, bf16_t* P, const bf16_t* wsb, const float* bs, const float* sg, const float* ssv, int ch0, int cstep, int h, int tid, int lane, int wid, bool dry) {
;     ...
;         for (int i = 0; i < 4; ++i) {
;             const int idx = tid + 512 * i, r = idx >> 4, c16 = idx & 15;
;             float pt = part[i];
;             pt += __shfl_xor(pt, 1); pt += __shfl_xor(pt, 2); pt += __shfl_xor(pt, 4); pt += __shfl_xor(pt, 8);
;             const float rv = __builtin_amdgcn_rsqf(pt * (1.0f / 1024.0f) + EPS);
;             const f32x4 g0 = sg0 * rv, g1 = sg1 * rv;
;             u32x4 gn;
;             gn.x = cvt_pk_bf16(bflo(gv[i].x) * g0[0], bfhi(gv[i].x) * g0[1]); gn.y = cvt_pk_bf16(bflo(gv[i].y) * g0[2], bfhi(gv[i].y) * g0[3]);
;             gn.z = cvt_pk_bf16(bflo(gv[i].z) * g1[0], bfhi(gv[i].z) * g1[1]); gn.w = cvt_pk_bf16(bflo(gv[i].w) * g1[2], bfhi(gv[i].w) * g1[3]);
;             *(LAS u32x4*)(GV + r * 288 + c16 * 16) = gn;
;             *(LAS u32x4*)(GU + r * 272 + c16 * 16) = gu[i];
;             *(LAS u32x4*)(SZ + r * 272 + c16 * 16) = sz[i];
;             if (first) *(LAS u32x4*)(WT + r * 272 + c16 * 16) = *(const u32x4*)(wsb + ((size_t)(h * 128 + r) * 128 + c16 * 8));
;         }
.LBB0_53:
	v_add_u32_e32 v156, v129, v136
	s_and_b64 vcc, exec, s[38:39]
	s_waitcnt lgkmcnt(0)
	s_nop 1
	v_add_f32_dpp v56, v122, v122 quad_perm:[1,0,3,2] row_mask:0xf bank_mask:0xf
	s_waitcnt lgkmcnt(0)
	s_nop 1
	v_add_f32_dpp v57, v56, v56 quad_perm:[2,3,0,1] row_mask:0xf bank_mask:0xf
	v_mov_b32_e32 v56, v57
	s_waitcnt lgkmcnt(0)
	s_nop 1
	v_add_f32_dpp v57, v56, v56 row_half_mirror row_mask:0xf bank_mask:0xf
	v_mov_b32_e32 v56, v57
	s_waitcnt lgkmcnt(0)
	s_nop 1
	v_add_f32_dpp v57, v56, v56 row_mirror row_mask:0xf bank_mask:0xf
	v_mov_b32_e32 v56, v57
	v_fmamk_f32 v56, v56, 0x3a800000, v217
	v_rsq_f32_e32 v56, v56
	s_nop 0
	v_pk_mul_f32 v[58:59], v[54:55], v[56:57] op_sel_hi:[1,0]
	v_pk_mul_f32 v[60:61], v[52:53], v[56:57] op_sel_hi:[1,0]
	v_pk_mul_f32 v[62:63], v[50:51], v[56:57] op_sel_hi:[1,0]
	v_pk_mul_f32 v[64:65], v[48:49], v[56:57] op_sel_hi:[1,0]
	v_lshlrev_b32_e32 v56, 16, v32
	v_and_b32_e32 v57, 0xffff0000, v32
	v_mul_f32_e32 v56, v60, v56
	v_mul_f32_e32 v57, v61, v57
	v_cvt_pk_bf16_f32 v56, v56, v57
	v_lshlrev_b32_e32 v57, 16, v33
	v_mul_f32_e32 v57, v58, v57
	v_and_b32_e32 v58, 0xffff0000, v33
	v_mul_f32_e32 v58, v59, v58
	v_cvt_pk_bf16_f32 v57, v57, v58
	v_lshlrev_b32_e32 v58, 16, v34
	v_and_b32_e32 v59, 0xffff0000, v34
	v_mul_f32_e32 v58, v64, v58
	v_mul_f32_e32 v59, v65, v59
	v_cvt_pk_bf16_f32 v58, v58, v59
	v_lshlrev_b32_e32 v59, 16, v35
	v_mul_f32_e32 v59, v62, v59
	v_and_b32_e32 v60, 0xffff0000, v35
	v_mul_f32_e32 v60, v63, v60
	v_cvt_pk_bf16_f32 v59, v59, v60
	ds_write_b128 v151, v[56:59]
	v_add_u32_e32 v56, v130, v136
	ds_write_b128 v156, v[24:27]
	ds_write_b128 v56, v[28:31]
	s_cbranch_vccnz .LBB0_55
	global_load_dwordx4 v[56:59], v[104:105], off
	v_add_u32_e32 v60, v128, v136
	s_waitcnt vmcnt(0)
	ds_write_b128 v60, v[56:59] offset:36864
.LBB0_55:
	v_add_u32_e32 v157, v129, v137
	s_and_b64 vcc, exec, s[38:39]
	s_waitcnt lgkmcnt(0)
	s_nop 1
	v_add_f32_dpp v56, v123, v123 quad_perm:[1,0,3,2] row_mask:0xf bank_mask:0xf
	s_waitcnt lgkmcnt(0)
	s_nop 1
	v_add_f32_dpp v57, v56, v56 quad_perm:[2,3,0,1] row_mask:0xf bank_mask:0xf
	v_mov_b32_e32 v56, v57
	s_waitcnt lgkmcnt(0)
	s_nop 1
	v_add_f32_dpp v57, v56, v56 row_half_mirror row_mask:0xf bank_mask:0xf
	v_mov_b32_e32 v56, v57
	s_waitcnt lgkmcnt(0)
	s_nop 1
	v_add_f32_dpp v57, v56, v56 row_mirror row_mask:0xf bank_mask:0xf
	v_mov_b32_e32 v56, v57
	v_fmamk_f32 v56, v56, 0x3a800000, v217
	v_rsq_f32_e32 v56, v56
	s_nop 0
	v_pk_mul_f32 v[58:59], v[54:55], v[56:57] op_sel_hi:[1,0]
	v_pk_mul_f32 v[60:61], v[52:53], v[56:57] op_sel_hi:[1,0]
	v_pk_mul_f32 v[62:63], v[50:51], v[56:57] op_sel_hi:[1,0]
	v_pk_mul_f32 v[64:65], v[48:49], v[56:57] op_sel_hi:[1,0]
	v_lshlrev_b32_e32 v56, 16, v44
	v_and_b32_e32 v57, 0xffff0000, v44
	v_mul_f32_e32 v56, v60, v56
	v_mul_f32_e32 v57, v61, v57
	v_cvt_pk_bf16_f32 v56, v56, v57
	v_lshlrev_b32_e32 v57, 16, v45
	v_mul_f32_e32 v57, v58, v57
	v_and_b32_e32 v58, 0xffff0000, v45
	v_mul_f32_e32 v58, v59, v58
	v_cvt_pk_bf16_f32 v57, v57, v58
	v_lshlrev_b32_e32 v58, 16, v46
	v_and_b32_e32 v59, 0xffff0000, v46
	v_mul_f32_e32 v58, v64, v58
	v_mul_f32_e32 v59, v65, v59
	v_cvt_pk_bf16_f32 v58, v58, v59
	v_lshlrev_b32_e32 v59, 16, v47
	v_mul_f32_e32 v59, v62, v59
	v_and_b32_e32 v60, 0xffff0000, v47
	v_mul_f32_e32 v60, v63, v60
	v_cvt_pk_bf16_f32 v59, v59, v60
	ds_write_b128 v152, v[56:59]
	v_add_u32_e32 v56, v130, v137
	ds_write_b128 v157, v[36:39]
	ds_write_b128 v56, v[40:43]
	s_cbranch_vccnz .LBB0_57
	global_load_dwordx4 v[56:59], v[106:107], off
	v_add_u32_e32 v60, v128, v137
	s_waitcnt vmcnt(0)
	ds_write_b128 v60, v[56:59] offset:36864
